# weight converter: global (not flat) loads, all 8 gain loads hoisted next to the data loads, chunk index fetched one chunk ahead
# baseline (speedup 1.0000x reference)
; #define XLAS __attribute__((address_space(3)))
; __device__ __forceinline__ void cvt_dyn(PP p, float* tile, const int tid_, const int lo, const int hi, unsigned* ctr) {
;     volatile XLAS unsigned* s_chunk_p = (volatile XLAS unsigned*)&ctl_words + 3;
;     for (;;) {
;         if (tid_ == 0) *s_chunk_p = atomicAdd(ctr, (unsigned)CVT_CH);
;         __syncthreads();
;         const int base = lo + (int)*s_chunk_p;
;         __syncthreads();
;         if (base >= hi) break;
;         cvt_range(p, tile, tid_, base, base + CVT_CH < hi ? base + CVT_CH : hi, 0, 1);
.LBB0_48:
	v_readlane_b32 s2, v253, 31
	v_cmp_ne_u32_e32 vcc, s16, v227
	v_readlane_b32 s3, v253, 32
	s_and_b64 s[2:3], s[2:3], vcc
	v_mov_b32_e32 v0, v226
	s_andn2_b64 vcc, exec, s[2:3]
	s_cbranch_vccnz .LBB0_224
	s_load_dwordx2 s[2:3], s[0:1], 0x98
	v_readlane_b32 s4, v253, 56
	s_waitcnt lgkmcnt(0)
	v_lshlrev_b32_e32 v2, 2, v0
	v_readlane_b32 s5, v253, 57
	v_and_b32_e32 v68, 60, v2
	s_waitcnt lgkmcnt(0)
	s_add_u32 s4, s2, s4
	s_addc_u32 s5, s3, s5
	v_bfe_u32 v2, v0, 2, 1
	s_add_u32 s6, s4, 0x296e0084
	v_sub_co_u32_e32 v69, vcc, 0, v2
	s_addc_u32 s7, s5, 0
	s_nop 0
	v_subb_co_u32_e64 v71, s[4:5], 0, 0, vcc
	v_cmp_eq_u32_e64 s[50:51], 0, v0
	v_ashrrev_i32_e32 v66, 4, v0
	v_ashrrev_i32_e32 v77, 3, v0
	v_lshlrev_b32_e32 v0, 3, v0
	s_movk_i32 s4, 0x104
	v_and_b32_e32 v70, 56, v0
	v_mul_lo_u32 v78, v66, s4
	v_lshl_add_u32 v76, v68, 2, 16
	v_lshl_add_u32 v0, v77, 2, 16
	v_add_u32_e32 v2, 0x2080, v78
	v_add_u32_e32 v3, 0x4100, v78
	v_mul_u32_u24_e32 v4, 0x104, v70
	v_ashrrev_i32_e32 v67, 31, v66
	v_add_u32_e32 v79, v76, v2
	v_add_u32_e32 v80, v76, v3
	v_add_u32_e32 v81, v0, v4
	v_mov_b32_e32 v119, 2
	s_and_saveexec_b64 s[8:9], s[50:51]
	s_cbranch_execz .LBB0_58
	global_atomic_add v118, v1, v119, s[6:7] sc0
	s_waitcnt vmcnt(0)
	s_branch .Lcv_top2
.Lcv_emitb_tail:
	s_waitcnt lgkmcnt(0)
	s_barrier
	ds_read2_b32 v[4:5], v81 offset1:65
	ds_read2_b32 v[6:7], v81 offset0:130 offset1:195
	ds_read2_b32 v[8:9], v12 offset0:4 offset1:69
	ds_read2_b32 v[10:11], v12 offset0:134 offset1:199
	v_add_u32_e32 v2, s16, v77
	v_mad_i64_i32 v[2:3], s[4:5], v2, s5, 0
	v_lshl_add_u64 v[2:3], v[2:3], 1, s[18:19]
	v_lshl_add_u64 v[26:27], s[20:21], 1, v[2:3]
	s_waitcnt lgkmcnt(3)
	v_cvt_pk_bf16_f32 v2, v4, v5
	s_waitcnt lgkmcnt(2)
	v_cvt_pk_bf16_f32 v3, v6, v7
	s_waitcnt lgkmcnt(1)
	v_cvt_pk_bf16_f32 v4, v8, v9
	s_waitcnt lgkmcnt(0)
	v_cvt_pk_bf16_f32 v5, v10, v11
	ds_read2_b32 v[8:9], v13 offset0:64 offset1:129
	ds_read2_b32 v[10:11], v15 offset0:66 offset1:131
	ds_read2_b32 v[12:13], v16 offset0:68 offset1:133
	ds_read2_b32 v[14:15], v18 offset0:70 offset1:135
	v_lshl_add_u64 v[6:7], v[26:27], 0, v[0:1]
	global_store_dwordx4 v[6:7], v[2:5], off
	s_waitcnt lgkmcnt(3)
	s_nop 0
	v_cvt_pk_bf16_f32 v2, v8, v9
	s_waitcnt lgkmcnt(2)
	v_cvt_pk_bf16_f32 v3, v10, v11
	s_waitcnt lgkmcnt(1)
	v_cvt_pk_bf16_f32 v4, v12, v13
	s_waitcnt lgkmcnt(0)
	v_cvt_pk_bf16_f32 v5, v14, v15
	ds_read2_b32 v[8:9], v19 offset0:128 offset1:193
	ds_read2_b32 v[10:11], v17 offset0:2 offset1:67
	ds_read2_b32 v[12:13], v17 offset0:132 offset1:197
	ds_read2_b32 v[14:15], v20 offset0:6 offset1:71
	global_store_dwordx4 v[6:7], v[2:5], off offset:128
	s_waitcnt lgkmcnt(3)
	s_nop 0
	v_cvt_pk_bf16_f32 v2, v8, v9
	s_waitcnt lgkmcnt(2)
	v_cvt_pk_bf16_f32 v3, v10, v11
	s_waitcnt lgkmcnt(1)
	v_cvt_pk_bf16_f32 v4, v12, v13
	s_waitcnt lgkmcnt(0)
	v_cvt_pk_bf16_f32 v5, v14, v15
	ds_read2_b32 v[8:9], v21 offset0:64 offset1:129
	ds_read2_b32 v[10:11], v22 offset0:66 offset1:131
	ds_read2_b32 v[12:13], v23 offset0:68 offset1:133
	ds_read2_b32 v[14:15], v24 offset0:70 offset1:135
	global_store_dwordx4 v[6:7], v[2:5], off offset:256
	s_waitcnt lgkmcnt(3)
	s_nop 0
	v_cvt_pk_bf16_f32 v2, v8, v9
	s_waitcnt lgkmcnt(2)
	v_cvt_pk_bf16_f32 v3, v10, v11
	s_waitcnt lgkmcnt(1)
	v_cvt_pk_bf16_f32 v4, v12, v13
	s_waitcnt lgkmcnt(0)
	v_cvt_pk_bf16_f32 v5, v14, v15
	global_store_dwordx4 v[6:7], v[2:5], off offset:384
	s_barrier

; __device__ __forceinline__ void cvt_dyn(PP p, float* tile, const int tid_, const int lo, const int hi, unsigned* ctr) {
;     ...
;         if (tid_ == 0) *s_chunk_p = atomicAdd(ctr, (unsigned)CVT_CH);
;         __syncthreads();
;         const int base = lo + (int)*s_chunk_p;
;         __syncthreads();
.LBB0_54:
	s_and_saveexec_b64 s[8:9], s[50:51]
	s_cbranch_execz .LBB0_58
	s_waitcnt vmcnt(4)
.Lcv_top2:
	v_mov_b32_e32 v0, v118
	ds_write_b32 v1, v0 offset:12
	global_atomic_add v118, v1, v119, s[6:7] sc0

; __device__ __forceinline__ void cvt_decode(PP p, int it, int n4, CvtItem& c) {
;     constexpr int I_GU = (NGU / 64) * (D / 256), I_DN = (D / 64) * (DFF / 256), I_IN = (NIN / 64) * (D / 256), I_UQ = (768 / 64) * (512 / 256),
;                   I_UKV = (1024 / 64) * (256 / 256), I_WO = (D / 64) * (D / 256);
;     constexpr int C0 = I_GU, C1 = C0 + I_DN, C2 = C1 + I_IN, C3 = C2 + I_UQ, C4 = C3 + I_UKV, C5 = C4 + I_WO, C6 = C5 + I_GU, C7 = C6 + I_DN;
;     const int l = it / C7; int r = it - l * C7;
;     char* lw = p->ws + (size_t)l * LW_SIZE;
;     c.gain = nullptr;
;     if (r < C0 || (r >= C5 && r < C6)) {
;         const bool second = r >= C5; if (second) r -= C5;
;         const int nb = r % (NGU / 64), kb = r / (NGU / 64);
;         ColGateUp cm{(second ? p->ffn2_wg : p->ffn1_wg) + (size_t)l * D * DFF, (second ? p->ffn2_wu : p->ffn1_wu) + (size_t)l * D * DFF};
;         c.src = cm(nb * 64 + n4); c.ldw = DFF; c.gain = (second ? p->ffn2_norm : p->ffn1_norm) + l * D; c.dst = (bf16_t*)(lw + (second ? LW_GU2 : LW_GU1)); c.K = D; c.n0 = nb * 64; c.k0 = kb * 256;
;     } else if (r < C1 || r >= C6) {
;         const bool second = r >= C6; r -= second ? C6 : C0;
;         const int nb = r % (D / 64), kb = r / (D / 64);
;         c.src = (second ? p->ffn2_wd : p->ffn1_wd) + (size_t)l * DFF * D + nb * 64 + n4; c.ldw = D; c.dst = (bf16_t*)(lw + (second ? LW_D2 : LW_D1)); c.K = DFF; c.n0 = nb * 64; c.k0 = kb * 256;
;     } else if (r < C2) {
;         r -= C1; const int nb = r % (NIN / 64), kb = r / (NIN / 64);
;         const int n = nb * 64 + n4;
;         const int col = win_col(n);
;         c.src = col >= 0 ? p->w_in + (size_t)l * D * ZW + col : nullptr; c.ldw = ZW; c.gain = p->attn_norm + l * D; c.dst = (bf16_t*)(lw + LW_IN); c.K = D; c.n0 = nb * 64; c.k0 = kb * 256;
;     } else if (r < C3) {
;         r -= C2; const int nb = r % (768 / 64), kb = r / (768 / 64);
;         c.src = p->w_uq + (size_t)l * 512 * 768 + nb * 64 + n4; c.ldw = 768; c.gain = p->q_norm + l * 512; c.dst = (bf16_t*)(lw + LW_UQ); c.K = 512; c.n0 = nb * 64; c.k0 = kb * 256;
;     } else if (r < C4) {
;         r -= C3; const int nb = r % (1024 / 64), kb = r / (1024 / 64);
;         c.src = p->w_ukv + (size_t)l * 256 * 1024 + nb * 64 + n4; c.ldw = 1024; c.gain = p->kv_norm + l * 256; c.dst = (bf16_t*)(lw + LW_UKV); c.K = 256; c.n0 = nb * 64; c.k0 = kb * 256;
;     } else {
.LBB0_124:
	s_or_b64 exec, exec, s[16:17]
	s_cmp_eq_u64 s[14:15], 0
	s_cbranch_scc1 .Lcv_ga_none
	v_mov_b32_e32 v116, v72
	v_mov_b32_e32 v117, v73
	v_lshl_add_u64 v[116:117], v[116:117], 2, s[14:15]
	global_load_dword v100, v[116:117], off
	global_load_dword v101, v[116:117], off offset:128
	global_load_dword v102, v[116:117], off offset:256
	global_load_dword v103, v[116:117], off offset:384
	global_load_dword v104, v[116:117], off offset:512
	global_load_dword v105, v[116:117], off offset:640
	global_load_dword v106, v[116:117], off offset:768
	global_load_dword v107, v[116:117], off offset:896
	s_branch .Lcv_ga_done
.Lcv_ga_none:
	v_mov_b32_e32 v100, 1.0
	v_mov_b32_e32 v101, 1.0
	v_mov_b32_e32 v102, 1.0
	v_mov_b32_e32 v103, 1.0
	v_mov_b32_e32 v104, 1.0
	v_mov_b32_e32 v105, 1.0
	v_mov_b32_e32 v106, 1.0
	v_mov_b32_e32 v107, 1.0
.Lcv_ga_done:
	s_add_i32 s11, s4, 1
	s_cmp_le_i32 s28, s11
	s_cbranch_scc1 .LBB0_192
	s_mul_hi_i32 s5, s11, 0x6830d6e5
	s_lshr_b32 s16, s5, 31
	s_ashr_i32 s5, s5, 11
	s_add_i32 s24, s5, s16
	s_mul_i32 s36, s24, 0xffffec58
	s_add_i32 s36, s36, s11
	s_ashr_i32 s25, s24, 31
	s_mul_i32 s11, s24, 0x9d40000
	s_mul_hi_i32 s5, s24, 0x9d40000
	s_add_u32 s11, s2, s11
	s_addc_u32 s29, s3, s5
	s_cmpk_lt_i32 s36, 0x580
	s_cselect_b64 s[16:17], -1, 0
	s_add_i32 s37, s36, 0xfffff498
	s_cmpk_lt_u32 s37, 0x580
	s_cselect_b64 s[18:19], -1, 0
	s_or_b64 s[16:17], s[16:17], s[18:19]
	s_andn2_b64 vcc, exec, s[16:17]
	s_mov_b64 s[30:31], -1
	s_cbranch_vccz .LBB0_173
	s_add_i32 s5, s36, 0xffffef18
	s_cmp_gt_u32 s5, 0xfffff757
	s_cbranch_scc0 .LBB0_170
	s_cmpk_gt_u32 s36, 0xa3f
	s_cbranch_scc0 .LBB0_136
	s_cmpk_gt_u32 s36, 0xa57
	s_cbranch_scc0 .LBB0_133
	s_cmpk_gt_u32 s36, 0xa67
	s_mov_b64 s[22:23], -1
	s_cbranch_scc0 .LBB0_131
	s_load_dwordx2 s[16:17], s[0:1], 0x60
	s_add_i32 s5, s36, 0xfffff598
	s_lshl_b64 s[18:19], s[24:25], 24
	v_lshlrev_b32_e32 v0, 2, v68
	s_mov_b64 s[22:23], 0
	s_waitcnt lgkmcnt(0)
	s_add_u32 s18, s16, s18
	s_addc_u32 s17, s17, s19
	s_lshl_b32 s16, s5, 6
	s_and_b32 s16, s16, 0x7c0
	s_lshl_b32 s19, s16, 2
	s_add_u32 s18, s18, s19
	s_addc_u32 s19, s17, 0
	v_lshl_add_u64 v[74:75], s[18:19], 0, v[0:1]
	s_add_u32 s18, s11, 0x5340000
	s_addc_u32 s19, s29, 0
	s_lshl_b32 s5, s5, 3
	s_and_b32 s20, s5, 0x7fffff00

.LBB0_191:
	s_or_b64 exec, exec, s[24:25]
	s_cmp_eq_u64 s[22:23], 0
	s_cbranch_scc1 .Lcv_gb_none
	v_add_u32_e32 v116, s20, v66
	v_ashrrev_i32_e32 v117, 31, v116
	v_lshl_add_u64 v[116:117], v[116:117], 2, s[22:23]
	global_load_dword v108, v[116:117], off
	global_load_dword v109, v[116:117], off offset:128
	global_load_dword v110, v[116:117], off offset:256
	global_load_dword v111, v[116:117], off offset:384
	global_load_dword v112, v[116:117], off offset:512
	global_load_dword v113, v[116:117], off offset:640
	global_load_dword v114, v[116:117], off offset:768
	global_load_dword v115, v[116:117], off offset:896
	s_branch .Lcv_gb_done
.Lcv_gb_none:
	v_mov_b32_e32 v108, 1.0
	v_mov_b32_e32 v109, 1.0
	v_mov_b32_e32 v110, 1.0
	v_mov_b32_e32 v111, 1.0
	v_mov_b32_e32 v112, 1.0
	v_mov_b32_e32 v113, 1.0
	v_mov_b32_e32 v114, 1.0
	v_mov_b32_e32 v115, 1.0
.Lcv_gb_done:
.LBB0_192:
	v_add_u32_e32 v74, v76, v78
	s_ashr_i32 s11, s10, 31
	s_waitcnt vmcnt(0) lgkmcnt(0)
	v_mul_f32_e32 v14, v100, v14
	v_mul_f32_e32 v15, v100, v15
	v_mul_f32_e32 v16, v100, v16
	v_mul_f32_e32 v17, v100, v17
	ds_write_b32 v74, v14
	ds_write_b32 v74, v15 offset:4
	ds_write_b32 v74, v16 offset:8
	ds_write_b32 v74, v17 offset:12
	v_mul_f32_e32 v2, v101, v2
	v_mul_f32_e32 v3, v101, v3
	v_mul_f32_e32 v4, v101, v4
	v_mul_f32_e32 v5, v101, v5
	ds_write_b32 v74, v2 offset:8320
	ds_write_b32 v74, v3 offset:8324
	ds_write_b32 v74, v4 offset:8328
	ds_write_b32 v74, v5 offset:8332
	v_mul_f32_e32 v22, v102, v22
	v_mul_f32_e32 v23, v102, v23
	v_mul_f32_e32 v24, v102, v24
	v_mul_f32_e32 v25, v102, v25
	ds_write_b32 v74, v22 offset:16640
	ds_write_b32 v74, v23 offset:16644
	ds_write_b32 v74, v24 offset:16648
	ds_write_b32 v74, v25 offset:16652
	v_mul_f32_e32 v6, v103, v6
	v_mul_f32_e32 v7, v103, v7
	v_mul_f32_e32 v8, v103, v8
	v_mul_f32_e32 v9, v103, v9
	ds_write_b32 v74, v6 offset:24960
	ds_write_b32 v74, v7 offset:24964
	ds_write_b32 v74, v8 offset:24968
	ds_write_b32 v74, v9 offset:24972
	v_mul_f32_e32 v26, v104, v26
	v_mul_f32_e32 v27, v104, v27
	v_mul_f32_e32 v28, v104, v28
	v_mul_f32_e32 v29, v104, v29
	ds_write_b32 v74, v26 offset:33280
	ds_write_b32 v74, v27 offset:33284
	ds_write_b32 v74, v28 offset:33288
	ds_write_b32 v74, v29 offset:33292
	v_mul_f32_e32 v18, v105, v18
	v_mul_f32_e32 v19, v105, v19
	v_mul_f32_e32 v20, v105, v20
	v_mul_f32_e32 v21, v105, v21
	ds_write_b32 v74, v18 offset:41600
	ds_write_b32 v74, v19 offset:41604
	ds_write_b32 v74, v20 offset:41608
	ds_write_b32 v74, v21 offset:41612
	v_mul_f32_e32 v30, v106, v30
	v_mul_f32_e32 v31, v106, v31
	v_mul_f32_e32 v32, v106, v32
	v_mul_f32_e32 v33, v106, v33
	ds_write_b32 v74, v30 offset:49920
	ds_write_b32 v74, v31 offset:49924
	ds_write_b32 v74, v32 offset:49928
	ds_write_b32 v74, v33 offset:49932
	v_mul_f32_e32 v10, v107, v10
	v_mul_f32_e32 v11, v107, v11
	v_mul_f32_e32 v12, v107, v12
	v_mul_f32_e32 v13, v107, v13
	ds_write_b32 v74, v10 offset:58240
	ds_write_b32 v74, v11 offset:58244
	ds_write_b32 v74, v12 offset:58248
	ds_write_b32 v74, v13 offset:58252
	v_add_u32_e32 v0, s88, v77
	v_ashrrev_i32_e32 v2, 31, v0
	v_mul_lo_u32 v2, s12, v2
	v_mul_lo_u32 v15, s13, v0
	v_mad_u64_u32 v[12:13], s[12:13], s12, v0, 0
	v_add3_u32 v13, v13, v2, v15
	v_lshl_add_u64 v[16:17], v[12:13], 1, s[8:9]
	v_add_u32_e32 v12, 0x400, v81
	s_waitcnt lgkmcnt(0)
	s_barrier
	ds_read2_b32 v[18:19], v81 offset1:65
	ds_read2_b32 v[22:23], v81 offset0:130 offset1:195
	ds_read2_b32 v[24:25], v12 offset0:4 offset1:69
	ds_read2_b32 v[26:27], v12 offset0:134 offset1:199
	v_lshl_add_u64 v[16:17], s[10:11], 1, v[16:17]
	v_lshlrev_b32_e32 v0, 1, v70
	s_waitcnt lgkmcnt(3)
	v_cvt_pk_bf16_f32 v20, v18, v19
	v_lshl_add_u64 v[30:31], v[16:17], 0, v[0:1]
	v_add_u32_e32 v13, 0x4000, v81
	v_add_u32_e32 v15, 0x4200, v81
	v_add_u32_e32 v16, 0x4400, v81
	v_add_u32_e32 v18, 0x4600, v81
	s_waitcnt lgkmcnt(2)
	v_cvt_pk_bf16_f32 v21, v22, v23
	s_waitcnt lgkmcnt(1)
	v_cvt_pk_bf16_f32 v22, v24, v25
	s_waitcnt lgkmcnt(0)
	v_cvt_pk_bf16_f32 v23, v26, v27
	ds_read2_b32 v[24:25], v13 offset0:64 offset1:129
	ds_read2_b32 v[26:27], v15 offset0:66 offset1:131
	ds_read2_b32 v[28:29], v16 offset0:68 offset1:133
	ds_read2_b32 v[32:33], v18 offset0:70 offset1:135
	v_add_u32_e32 v19, 0x8000, v81
	v_add_u32_e32 v17, 0x8400, v81
	global_store_dwordx4 v[30:31], v[20:23], off
	s_add_i32 s14, s4, 2
	s_min_i32 s14, s14, s28
	s_waitcnt lgkmcnt(3)
	v_cvt_pk_bf16_f32 v22, v24, v25
	s_waitcnt lgkmcnt(2)
	v_cvt_pk_bf16_f32 v23, v26, v27
	s_waitcnt lgkmcnt(1)
	v_cvt_pk_bf16_f32 v24, v28, v29
	s_waitcnt lgkmcnt(0)
	v_cvt_pk_bf16_f32 v25, v32, v33
	ds_read2_b32 v[26:27], v19 offset0:128 offset1:193
	ds_read2_b32 v[28:29], v17 offset0:2 offset1:67
	ds_read2_b32 v[32:33], v17 offset0:132 offset1:197
	s_add_i32 s14, s14, -1
	v_add_u32_e32 v20, 0x8800, v81
	ds_read2_b32 v[72:73], v20 offset0:6 offset1:71
	global_store_dwordx4 v[30:31], v[22:25], off offset:128
	s_waitcnt lgkmcnt(3)
	v_cvt_pk_bf16_f32 v26, v26, v27
	s_waitcnt lgkmcnt(2)
	v_cvt_pk_bf16_f32 v27, v28, v29
	s_waitcnt lgkmcnt(1)
	v_cvt_pk_bf16_f32 v28, v32, v33
	s_waitcnt lgkmcnt(0)
	v_cvt_pk_bf16_f32 v29, v72, v73
	v_add_u32_e32 v21, 0xc200, v81
	v_add_u32_e32 v22, 0xc400, v81
	v_add_u32_e32 v23, 0xc600, v81
	v_add_u32_e32 v24, 0xc800, v81
	s_cmp_ge_i32 s4, s14
	ds_read2_b32 v[32:33], v21 offset0:64 offset1:129
	ds_read2_b32 v[72:73], v22 offset0:66 offset1:131
	ds_read2_b32 v[82:83], v23 offset0:68 offset1:133
	ds_read2_b32 v[84:85], v24 offset0:70 offset1:135
	global_store_dwordx4 v[30:31], v[26:29], off offset:256
	s_waitcnt lgkmcnt(3)
	s_nop 0
	v_cvt_pk_bf16_f32 v26, v32, v33
	s_waitcnt lgkmcnt(2)
	v_cvt_pk_bf16_f32 v27, v72, v73
	s_waitcnt lgkmcnt(1)
	v_cvt_pk_bf16_f32 v28, v82, v83
	s_waitcnt lgkmcnt(0)
	v_cvt_pk_bf16_f32 v29, v84, v85
	global_store_dwordx4 v[30:31], v[26:29], off offset:384
	s_barrier
; __global__ void __launch_bounds__(NTHREADS) mega(Params p_arg) {
;     ...
;                 float* ss = (float*)(p->ws + OFF_SS);
;                 float* xres = (float*)(p->ws + OFF_XRES);
;                 bf16_t* xb = (bf16_t*)(p->ws + OFF_XB);
;                 bf16_t* act = (bf16_t*)(p->ws + OFF_U);
;                 const char* lw = p->ws + (size_t)l * LW_SIZE;
;                 GemmDesc d0{}, d1{};
;                 int n0 = 0, n1 = 0;
;                 if (s == 0 || s == 6) {
;                     d0.A = xb; d0.Bt = (const bf16_t*)(lw + (s == 0 ? LW_GU1 : LW_GU2)); d0.nN = NGU / BM; d0.K = D; d0.epi = 0;
;                     d0.ssin = ss + (3 * l + (s == 0 ? 0 : 2)) * T; d0.outb = act; n0 = 32 * (NGU / BM);
;                 } else if (s == 1 || s == 7) {
;                     d0.A = act; d0.Bt = (const bf16_t*)(lw + (s == 1 ? LW_D1 : LW_D2)); d0.nN = D / BM; d0.K = DFF; d0.epi = 1;
;                     d0.xin = (l == 0 && s == 1) ? p->x : xres; d0.outf = xres; d0.outb = xb; d0.ssout = ss + (3 * l + (s == 1 ? 1 : 3)) * T; d0.scale = 0.5f;
;                     n0 = 32 * (D / BM);
;                 } else if (s == 2) {
;                     d0.A = xb; d0.Bt = (const bf16_t*)(lw + LW_IN); d0.nN = NIN / BM; d0.K = D; d0.epi = 2;
;                     d0.ssin = ss + (3 * l + 1) * T; d0.ws = p->ws; d0.layer = l; n0 = 32 * (NIN / BM);
;                 } else if (s == 3) {
;                     d0.A = (const bf16_t*)(p->ws + OFF_CQN); d0.Bt = (const bf16_t*)(lw + LW_UQ); d0.nN = 3; d0.K = 512; d0.epi = 3;
;                     d0.outb = (bf16_t*)(p->ws + OFF_QB); d0.ld = 768; d0.ssin = ss + (7 + 2 * l) * T; d0.scale = 1.0f / 512.0f; n0 = 96;
;                     d1.A = (const bf16_t*)(p->ws + OFF_CKVN); d1.Bt = (const bf16_t*)(lw + LW_UKV); d1.nN = 4; d1.K = 256; d1.epi = 3;
;                     d1.outb = (bf16_t*)(p->ws + OFF_KVB); d1.ld = 1024; d1.ssin = ss + (8 + 2 * l) * T; d1.scale = 1.0f / 256.0f; n1 = 128;
;                 } else {
;                     d0.A = (const bf16_t*)(p->ws + OFF_OB); d0.Bt = (const bf16_t*)(lw + LW_WO); d0.nN = D / BM; d0.K = D; d0.epi = 1;
;                     d0.xin = xres; d0.outf = xres; d0.outb = xb; d0.ssout = ss + (3 * l + 2) * T; d0.scale = 1.0f; n0 = 32 * (D / BM);
;                 }
	s_cbranch_scc1 .LBB0_52
	s_ashr_i32 s21, s20, 31
	v_mul_f32_e32 v38, v108, v38
	v_mul_f32_e32 v39, v108, v39
	v_mul_f32_e32 v40, v108, v40
	v_mul_f32_e32 v41, v108, v41
	ds_write_b32 v74, v38
	ds_write_b32 v74, v39 offset:4
	ds_write_b32 v74, v40 offset:8
	ds_write_b32 v74, v41 offset:12
	v_mul_f32_e32 v34, v109, v34
	v_mul_f32_e32 v35, v109, v35
	v_mul_f32_e32 v36, v109, v36
	v_mul_f32_e32 v37, v109, v37
	ds_write_b32 v74, v34 offset:8320
	ds_write_b32 v74, v35 offset:8324
	ds_write_b32 v74, v36 offset:8328
	ds_write_b32 v74, v37 offset:8332
	v_mul_f32_e32 v46, v110, v46
	v_mul_f32_e32 v47, v110, v47
	v_mul_f32_e32 v48, v110, v48
	v_mul_f32_e32 v49, v110, v49
	ds_write_b32 v74, v46 offset:16640
	ds_write_b32 v74, v47 offset:16644
	ds_write_b32 v74, v48 offset:16648
	ds_write_b32 v74, v49 offset:16652
	v_mul_f32_e32 v42, v111, v42
	v_mul_f32_e32 v43, v111, v43
	v_mul_f32_e32 v44, v111, v44
	v_mul_f32_e32 v45, v111, v45
	ds_write_b32 v74, v42 offset:24960
	ds_write_b32 v74, v43 offset:24964
	ds_write_b32 v74, v44 offset:24968
	ds_write_b32 v74, v45 offset:24972
	v_mul_f32_e32 v58, v112, v58
	v_mul_f32_e32 v59, v112, v59
	v_mul_f32_e32 v60, v112, v60
	v_mul_f32_e32 v61, v112, v61
	ds_write_b32 v74, v58 offset:33280
	ds_write_b32 v74, v59 offset:33284
	ds_write_b32 v74, v60 offset:33288
	ds_write_b32 v74, v61 offset:33292
	v_mul_f32_e32 v50, v113, v50
	v_mul_f32_e32 v51, v113, v51
	v_mul_f32_e32 v52, v113, v52
	v_mul_f32_e32 v53, v113, v53
	ds_write_b32 v74, v50 offset:41600
	ds_write_b32 v74, v51 offset:41604
	ds_write_b32 v74, v52 offset:41608
	ds_write_b32 v74, v53 offset:41612
	v_mul_f32_e32 v62, v114, v62
	v_mul_f32_e32 v63, v114, v63
	v_mul_f32_e32 v64, v114, v64
	v_mul_f32_e32 v65, v114, v65
	ds_write_b32 v74, v62 offset:49920
	ds_write_b32 v74, v63 offset:49924
	ds_write_b32 v74, v64 offset:49928
	ds_write_b32 v74, v65 offset:49932
	v_mul_f32_e32 v54, v115, v54
	v_mul_f32_e32 v55, v115, v55
	v_mul_f32_e32 v56, v115, v56
	v_mul_f32_e32 v57, v115, v57
	ds_write_b32 v74, v54 offset:58240
	ds_write_b32 v74, v55 offset:58244
	ds_write_b32 v74, v56 offset:58248
	ds_write_b32 v74, v57 offset:58252
	s_branch .Lcv_emitb_tail
.LBB0_224:
	s_waitcnt vmcnt(0)
	v_readlane_b32 s2, v253, 52
	v_readlane_b32 s3, v253, 53
	s_mov_b64 s[4:5], -1
	s_xor_b64 s[2:3], s[2:3], -1
	v_writelane_b32 v253, s4, 52
	s_andn2_b64 vcc, exec, s[2:3]
	s_mov_b64 s[2:3], -1
	v_writelane_b32 v253, s5, 53
	s_cbranch_vccnz .LBB0_47
	s_and_b64 vcc, exec, s[48:49]
	s_cbranch_vccz .LBB0_694
	s_and_b64 vcc, exec, s[46:47]
	s_cbranch_vccz .LBB0_688
	v_readlane_b32 s2, v253, 26
	v_readlane_b32 s3, v253, 27
	s_andn2_b64 vcc, exec, s[2:3]
	s_cbranch_vccnz .LBB0_687
	v_readlane_b32 s4, v253, 29
	v_readlane_b32 s5, v253, 30
	s_mov_b64 s[2:3], -1
	s_and_b64 vcc, exec, s[4:5]
	s_cbranch_vccz .LBB0_382
	s_load_dwordx2 s[12:13], s[0:1], 0x98
	v_readlane_b32 s11, v253, 34
	s_mul_i32 s10, s11, 0x9d40000
	s_mov_b64 s[16:17], -1
	s_mov_b64 s[14:15], 0
	s_waitcnt lgkmcnt(0)
	s_add_u32 s4, s12, 0x29388000
	s_addc_u32 s5, s13, 0
	s_add_u32 s8, s12, 0x13a80000
	s_addc_u32 s9, s13, 0
	s_add_u32 s2, s12, 0x17a80000
	s_addc_u32 s3, s13, 0
	s_add_u32 s6, s12, 0x19a80000
	s_addc_u32 s7, s13, 0
	s_add_u32 s18, s12, s10
	s_mul_hi_u32 s10, s11, 0x9d40000
	s_addc_u32 s19, s13, s10
	s_mov_b64 s[10:11], 0
	v_writelane_b32 v254, s10, 12
	s_mov_b64 s[12:13], 0
	s_nop 0
	v_writelane_b32 v254, s11, 13
	v_readlane_b32 s10, v253, 28
	s_cmp_lt_i32 s10, 3
	s_mov_b64 s[10:11], 0
	s_cbranch_scc1 .LBB0_237
	v_readlane_b32 s12, v253, 28
	s_cmp_gt_i32 s12, 5
	s_cbranch_scc0 .LBB0_234
	s_mov_b64 s[16:17], 0
	s_mov_b64 s[10:11], -1
	s_cmp_gt_i32 s12, 6
	s_mov_b64 s[12:13], 0
	s_cbranch_scc0 .LBB0_233
	v_readlane_b32 s14, v253, 28
	s_cmp_eq_u32 s14, 7
	s_mov_b64 s[12:13], -1
	s_mov_b64 s[10:11], 0
	s_cselect_b64 s[14:15], -1, 0
